# in-proj K-loop: the two near-critical load segments (16 LDS reads + 2 DMAs) lightened - LDS read bases precomputed in four spare VGPRs instead of a VALU add per group, K-offset scalar bookkeeping move
# baseline (speedup 1.0000x reference)
; #define PG8_STAGE(bufoff, goff, voff) do { _Pragma("unroll") for (int _i = 0; _i < 2; ++_i) \
;         __builtin_amdgcn_raw_ptr_buffer_load_lds(R_##voff, (LAS void*)(lds + (bufoff) + ldsw + _i * 8192), 16, (int)(voff)[_i], (int)(goff), 0, 0); } while (0)
; #define PG8_WAIT_V(n) asm volatile("s_waitcnt vmcnt(" #n ")" ::: "memory")
; #define PG8_BAR __builtin_amdgcn_s_barrier()
; template <class Epi, class Sched, bool ALIGN_EPI, bool SP2>
; __device__ __forceinline__ void gemm_phase(LAS unsigned char* lds, const Gemm g, const Sched& S, const Epi& E, int tid_in) {
;     ...
;     unsigned cA = (unsigned)cur.pm * tstepA, cB = (unsigned)cur.pn * tstepB;
;     if constexpr (SP2) {
;         PG8_STAGE(PG8_SB(0, 0), cB, voffB); PG8_STAGE(PG8_SB(0, 1), cB + hstepB, voffB); PG8_STAGE(PG8_SA(0, 0), cA, voffA); PG8_STAGE(PG8_SA(0, 1), cA + hstepA, voffA);
;         if (wr == 1) PG8_BAR;
;         PG8_WAIT_V(2); PG8_BAR;
;         PG8_STAGE(PG8_SB(1, 0), cB + kstep, voffB); PG8_STAGE(PG8_SA(1, 0), cA + kstep, voffA); PG8_STAGE(PG8_SB(1, 1), cB + hstepB + kstep, voffB);
;         PG8_WAIT_V(6); PG8_BAR;
;     } else {
;         PG8_STAGE(PG8_SB(0, 0), cB, voffB); PG8_STAGE(PG8_SA(0, 0), cA, voffA); PG8_STAGE(PG8_SB(0, 1), cB + hstepB, voffB); PG8_STAGE(PG8_SA(0, 1), cA + hstepA, voffA);
;         if (wr == 1) PG8_BAR;
;         PG8_WAIT_V(4); PG8_BAR;
;         PG8_STAGE(PG8_SB(1, 0), cB + kstep, voffB); PG8_STAGE(PG8_SA(1, 0), cA + kstep, voffA); PG8_STAGE(PG8_SB(1, 1), cB + hstepB + kstep, voffB);
;         PG8_WAIT_V(6); PG8_BAR;
;     }
.LBB0_133:
	v_readlane_b32 s6, v255, 24
	v_readlane_b32 s7, v255, 25
	s_add_u32 s60, s6, 0x24000000
	s_addc_u32 s61, s7, 0
	s_add_u32 s34, s6, 0x29000000
	s_addc_u32 s50, s7, 0
	s_add_u32 s79, s6, 0x2b000000
	s_addc_u32 s84, s7, 0
	s_add_u32 s54, s6, 0x17100000
	s_addc_u32 s55, s7, 0
	s_add_i32 s85, s15, 0x18000
	s_or_b32 s5, s71, 0x80
	s_mov_b32 s46, s42
	s_mov_b32 s47, s43
	s_mov_b32 m0, s85
	s_add_i32 s93, s15, 0x1a000
	s_waitcnt vmcnt(2)
	s_barrier
	buffer_load_dwordx4 v188, s[44:47], s5 offen lds
	s_mov_b32 m0, s93
	s_add_i32 s94, s15, 0x8000
	buffer_load_dwordx4 v190, s[44:47], s5 offen lds
	s_or_b32 s5, s76, 0x80
	s_mov_b32 m0, s94
	s_add_i32 s95, s15, 0xa000
	buffer_load_dwordx4 v115, s[40:43], s5 offen lds
	s_mov_b32 m0, s95
	s_add_i32 s67, s15, 0x1c000
	buffer_load_dwordx4 v189, s[40:43], s5 offen lds
	s_or_b32 s5, s71, 0x40080
	s_mov_b32 m0, s67
	s_add_i32 s49, s15, 0x1e000
	buffer_load_dwordx4 v188, s[44:47], s5 offen lds
	s_mov_b32 m0, s49
	v_bfe_u32 v192, v0, 4, 2
	buffer_load_dwordx4 v190, s[44:47], s5 offen lds
	v_and_b32_e32 v191, 15, v0
	v_lshlrev_b32_e32 v2, 4, v192
	v_lshlrev_b32_e32 v0, 2, v0
	s_and_b32 s3, s3, 3
	s_lshl_b32 s52, s4, 6
	v_lshl_or_b32 v2, v191, 6, v2
	s_lshl_b32 s4, s4, 13
	v_and_b32_e32 v0, 32, v0
	v_bitop3_b32 v3, v2, s4, v0 bitop3:0xde
	s_lshl_b32 s4, s3, 12
	s_lshl_b32 s53, s3, 5
	s_add_i32 s8, s15, 0xc000
	s_cmpk_lt_u32 s2, 0x100
	s_waitcnt vmcnt(6)
	s_cselect_b64 s[2:3], -1, 0
	v_bitop3_b32 v0, v2, s4, v0 bitop3:0xde
	v_writelane_b32 v255, s2, 30
	s_add_i32 s16, s15, 0xe000
	s_mov_b32 s9, 0
	v_writelane_b32 v255, s3, 31
	v_add_u32_e32 v193, 0, v0
	v_add_u32_e32 v224, 0x10000, v193
	v_add_u32_e32 v225, 0x14000, v193
	v_add_u32_e32 v226, 0x18000, v193
	v_add_u32_e32 v227, 0x1c000, v193
	v_add_u32_e32 v194, 0, v3
	s_mov_b32 s56, s25
	s_barrier
	s_branch .LBB0_136

; #define PG8_STAGE(bufoff, goff, voff) do { _Pragma("unroll") for (int _i = 0; _i < 2; ++_i) \
;         __builtin_amdgcn_raw_ptr_buffer_load_lds(R_##voff, (LAS void*)(lds + (bufoff) + ldsw + _i * 8192), 16, (int)(voff)[_i], (int)(goff), 0, 0); } while (0)
; #define PG8_WAIT_V(n) asm volatile("s_waitcnt vmcnt(" #n ")" ::: "memory")
; #define PG8_WAIT_L(n) asm volatile("s_waitcnt lgkmcnt(" #n ")" ::: "memory")
; #define PG8_BAR __builtin_amdgcn_s_barrier()
; #define PG8_SCHED __builtin_amdgcn_sched_barrier(0)
; template <class Epi, class Sched, bool ALIGN_EPI, bool SP2>
; __device__ __forceinline__ void gemm_phase(LAS unsigned char* lds, const Gemm g, const Sched& S, const Epi& E, int tid_in) {
;     ...
;             PG8_LDB(B0, 0, 0); PG8_LDB(B1, 0, 1); PG8_SCHED; PG8_LDA(At, 0, 0); PG8_STAGE(PG8_SA(1, 1), a1 + hstepA, voffA);
;             PG8_WAIT_V(8); PG8_WAIT_L(0); PG8_BAR; PG8_MMA(0, 0, At, B0); PG8_MMA(0, 1, At, B1); PG8_BAR; PG8_SCHED;
;             PG8_LDA(At, 0, 1); PG8_STAGE(PG8_SB(0, 0), b2, voffB); PG8_STAGE(PG8_SB(0, 1), b2 + hstepB, voffB); PG8_STAGE(PG8_SA(0, 0), a2, voffA);
;             PG8_WAIT_V(8); PG8_WAIT_L(0); PG8_BAR; PG8_MMA(1, 0, At, B0); PG8_MMA(1, 1, At, B1); PG8_BAR; PG8_SCHED;
.LBB0_137:
	ds_read_b128 v[2:5], v224
	ds_read_b128 v[6:9], v224 offset:1024
	ds_read_b128 v[10:13], v224 offset:2048
	ds_read_b128 v[14:17], v224 offset:3072
	ds_read_b128 v[18:21], v225
	ds_read_b128 v[22:25], v225 offset:1024
	ds_read_b128 v[26:29], v225 offset:2048
	ds_read_b128 v[30:33], v225 offset:3072
	s_mov_b32 m0, s8
	ds_read_b128 v[164:167], v194
	ds_read_b128 v[168:171], v194 offset:1024
	ds_read_b128 v[172:175], v194 offset:2048
	ds_read_b128 v[176:179], v194 offset:3072
	ds_read_b128 v[180:183], v194 offset:4096
	ds_read_b128 v[184:187], v194 offset:5120
	ds_read_b128 v[196:199], v194 offset:6144
	ds_read_b128 v[200:203], v194 offset:7168
	buffer_load_dwordx4 v115, s[40:43], s4 offen lds
	s_mov_b32 m0, s16
	s_nop 0
	buffer_load_dwordx4 v189, s[40:43], s4 offen lds
	s_waitcnt vmcnt(8)
	s_waitcnt lgkmcnt(0)
	s_barrier
	s_waitcnt lgkmcnt(7)
	v_mfma_f32_16x16x32_bf16 v[46:49], v[2:5], v[164:167], v[46:49]
	v_mfma_f32_16x16x32_bf16 v[42:45], v[10:13], v[164:167], v[42:45]
	s_waitcnt lgkmcnt(5)
	v_mfma_f32_16x16x32_bf16 v[160:163], v[2:5], v[172:175], v[160:163]
	v_mfma_f32_16x16x32_bf16 v[156:159], v[10:13], v[172:175], v[156:159]
	s_waitcnt lgkmcnt(3)
	v_mfma_f32_16x16x32_bf16 v[144:147], v[2:5], v[180:183], v[144:147]
	v_mfma_f32_16x16x32_bf16 v[140:143], v[10:13], v[180:183], v[140:143]
	s_waitcnt lgkmcnt(1)
	v_mfma_f32_16x16x32_bf16 v[62:65], v[2:5], v[196:199], v[62:65]
	v_mfma_f32_16x16x32_bf16 v[58:61], v[10:13], v[196:199], v[58:61]
	v_mfma_f32_16x16x32_bf16 v[46:49], v[6:9], v[168:171], v[46:49]
	v_mfma_f32_16x16x32_bf16 v[42:45], v[14:17], v[168:171], v[42:45]
	v_mfma_f32_16x16x32_bf16 v[160:163], v[6:9], v[176:179], v[160:163]
	v_mfma_f32_16x16x32_bf16 v[156:159], v[14:17], v[176:179], v[156:159]
	v_mfma_f32_16x16x32_bf16 v[144:147], v[6:9], v[184:187], v[144:147]
	v_mfma_f32_16x16x32_bf16 v[140:143], v[14:17], v[184:187], v[140:143]
	s_waitcnt lgkmcnt(0)
	v_mfma_f32_16x16x32_bf16 v[62:65], v[6:9], v[200:203], v[62:65]
	v_mfma_f32_16x16x32_bf16 v[58:61], v[14:17], v[200:203], v[58:61]
	v_mfma_f32_16x16x32_bf16 v[38:41], v[18:21], v[164:167], v[38:41]
	v_mfma_f32_16x16x32_bf16 v[34:37], v[26:29], v[164:167], v[34:37]
	v_mfma_f32_16x16x32_bf16 v[152:155], v[18:21], v[172:175], v[152:155]
	v_mfma_f32_16x16x32_bf16 v[148:151], v[26:29], v[172:175], v[148:151]
	v_mfma_f32_16x16x32_bf16 v[136:139], v[18:21], v[180:183], v[136:139]
	v_mfma_f32_16x16x32_bf16 v[132:135], v[26:29], v[180:183], v[132:135]
	v_mfma_f32_16x16x32_bf16 v[54:57], v[18:21], v[196:199], v[54:57]
	v_mfma_f32_16x16x32_bf16 v[50:53], v[26:29], v[196:199], v[50:53]
	v_mfma_f32_16x16x32_bf16 v[38:41], v[22:25], v[168:171], v[38:41]
	v_mfma_f32_16x16x32_bf16 v[34:37], v[30:33], v[168:171], v[34:37]
	v_mfma_f32_16x16x32_bf16 v[152:155], v[22:25], v[176:179], v[152:155]
	v_mfma_f32_16x16x32_bf16 v[148:151], v[30:33], v[176:179], v[148:151]
	v_mfma_f32_16x16x32_bf16 v[136:139], v[22:25], v[184:187], v[136:139]
	v_mfma_f32_16x16x32_bf16 v[132:135], v[30:33], v[184:187], v[132:135]
	v_mfma_f32_16x16x32_bf16 v[54:57], v[22:25], v[200:203], v[54:57]
	v_mfma_f32_16x16x32_bf16 v[50:53], v[30:33], v[200:203], v[50:53]
	s_barrier
	s_add_i32 s11, s4, 0xfff00080
	s_cmp_eq_u32 s10, 60
	s_cselect_b32 s13, s3, s11
	s_cselect_b32 s12, s2, s5
	s_or_b32 s11, s13, 0x80
	s_mov_b32 m0, s68
	s_mov_b32 s46, s42
	s_mov_b32 s47, s43
	ds_read_b128 v[164:167], v194 offset:16384
	ds_read_b128 v[168:171], v194 offset:17408
	ds_read_b128 v[172:175], v194 offset:18432
	ds_read_b128 v[176:179], v194 offset:19456
	ds_read_b128 v[180:183], v194 offset:20480
	ds_read_b128 v[184:187], v194 offset:21504
	ds_read_b128 v[196:199], v194 offset:22528
	ds_read_b128 v[200:203], v194 offset:23552
	buffer_load_dwordx4 v188, s[44:47], s12 offen lds
	s_mov_b32 m0, s69
	s_add_i32 s14, s12, 0x40000
	buffer_load_dwordx4 v190, s[44:47], s12 offen lds
	s_mov_b32 m0, s70
	s_nop 0
	buffer_load_dwordx4 v188, s[44:47], s14 offen lds
	s_mov_b32 m0, s72
	s_nop 0
	buffer_load_dwordx4 v190, s[44:47], s14 offen lds
	s_mov_b32 m0, s15
	s_nop 0
	buffer_load_dwordx4 v115, s[40:43], s13 offen lds
	s_mov_b32 m0, s73
	s_nop 0
	buffer_load_dwordx4 v189, s[40:43], s13 offen lds
	s_waitcnt vmcnt(8)
	s_waitcnt lgkmcnt(0)
	s_barrier
	s_waitcnt lgkmcnt(7)
	v_mfma_f32_16x16x32_bf16 v[128:131], v[2:5], v[164:167], v[128:131]
	v_mfma_f32_16x16x32_bf16 v[124:127], v[10:13], v[164:167], v[124:127]
	s_waitcnt lgkmcnt(5)
	v_mfma_f32_16x16x32_bf16 v[110:113], v[2:5], v[172:175], v[110:113]
	v_mfma_f32_16x16x32_bf16 v[106:109], v[10:13], v[172:175], v[106:109]
	s_waitcnt lgkmcnt(3)
	v_mfma_f32_16x16x32_bf16 v[94:97], v[2:5], v[180:183], v[94:97]
	v_mfma_f32_16x16x32_bf16 v[90:93], v[10:13], v[180:183], v[90:93]
	s_waitcnt lgkmcnt(1)
	v_mfma_f32_16x16x32_bf16 v[2:5], v[2:5], v[196:199], v[78:81]
	v_mfma_f32_16x16x32_bf16 v[128:131], v[6:9], v[168:171], v[128:131]
	v_mfma_f32_16x16x32_bf16 v[124:127], v[14:17], v[168:171], v[124:127]
	v_mfma_f32_16x16x32_bf16 v[110:113], v[6:9], v[176:179], v[110:113]
	v_mfma_f32_16x16x32_bf16 v[106:109], v[14:17], v[176:179], v[106:109]
	v_mfma_f32_16x16x32_bf16 v[94:97], v[6:9], v[184:187], v[94:97]
	v_mfma_f32_16x16x32_bf16 v[90:93], v[14:17], v[184:187], v[90:93]
	s_waitcnt lgkmcnt(0)
	v_mfma_f32_16x16x32_bf16 v[2:5], v[6:9], v[200:203], v[2:5]
	v_mfma_f32_16x16x32_bf16 v[6:9], v[10:13], v[196:199], v[74:77]
	v_mfma_f32_16x16x32_bf16 v[6:9], v[14:17], v[200:203], v[6:9]
	v_mfma_f32_16x16x32_bf16 v[74:77], v[18:21], v[172:175], v[102:105]
	v_mfma_f32_16x16x32_bf16 v[102:105], v[22:25], v[176:179], v[74:77]
	v_mfma_f32_16x16x32_bf16 v[74:77], v[26:29], v[172:175], v[98:101]
	v_mfma_f32_16x16x32_bf16 v[98:101], v[30:33], v[176:179], v[74:77]
	v_mfma_f32_16x16x32_bf16 v[74:77], v[18:21], v[180:183], v[86:89]
	v_mfma_f32_16x16x32_bf16 v[10:13], v[18:21], v[164:167], v[120:123]
	v_mfma_f32_16x16x32_bf16 v[86:89], v[22:25], v[184:187], v[74:77]
	v_mfma_f32_16x16x32_bf16 v[74:77], v[26:29], v[180:183], v[82:85]
	v_mfma_f32_16x16x32_bf16 v[18:21], v[18:21], v[196:199], v[70:73]
	v_mfma_f32_16x16x32_bf16 v[10:13], v[22:25], v[168:171], v[10:13]
	v_mfma_f32_16x16x32_bf16 v[14:17], v[26:29], v[164:167], v[116:119]
	v_mfma_f32_16x16x32_bf16 v[82:85], v[30:33], v[184:187], v[74:77]
	v_mfma_f32_16x16x32_bf16 v[18:21], v[22:25], v[200:203], v[18:21]
	v_mfma_f32_16x16x32_bf16 v[22:25], v[26:29], v[196:199], v[66:69]
	v_mfma_f32_16x16x32_bf16 v[14:17], v[30:33], v[168:171], v[14:17]
	v_mfma_f32_16x16x32_bf16 v[22:25], v[30:33], v[200:203], v[22:25]
	s_barrier
; #define PG8_STAGE(bufoff, goff, voff) do { _Pragma("unroll") for (int _i = 0; _i < 2; ++_i) \
;         __builtin_amdgcn_raw_ptr_buffer_load_lds(R_##voff, (LAS void*)(lds + (bufoff) + ldsw + _i * 8192), 16, (int)(voff)[_i], (int)(goff), 0, 0); } while (0)
; #define PG8_WAIT_V(n) asm volatile("s_waitcnt vmcnt(" #n ")" ::: "memory")
; #define PG8_WAIT_L(n) asm volatile("s_waitcnt lgkmcnt(" #n ")" ::: "memory")
; #define PG8_BAR __builtin_amdgcn_s_barrier()
; #define PG8_SCHED __builtin_amdgcn_sched_barrier(0)
; template <class Epi, class Sched, bool ALIGN_EPI, bool SP2>
; __device__ __forceinline__ void gemm_phase(LAS unsigned char* lds, const Gemm g, const Sched& S, const Epi& E, int tid_in) {
;     ...
;             PG8_LDB(B0, 1, 0); PG8_LDB(B1, 1, 1); PG8_SCHED; PG8_LDA(At, 1, 0); PG8_STAGE(PG8_SA(0, 1), a2 + hstepA, voffA);
;             PG8_WAIT_V(8); PG8_WAIT_L(0); PG8_BAR; PG8_MMA(0, 0, At, B0); PG8_MMA(0, 1, At, B1); PG8_BAR; PG8_SCHED;
;             PG8_LDA(At, 1, 1); PG8_STAGE(PG8_SB(1, 0), b3, voffB); PG8_STAGE(PG8_SB(1, 1), b3 + hstepB, voffB); PG8_STAGE(PG8_SA(1, 0), a3, voffA);
;             PG8_WAIT_V(8); PG8_WAIT_L(0); PG8_BAR; PG8_MMA(1, 0, At, B0); PG8_MMA(1, 1, At, B1); PG8_BAR; PG8_SCHED;
	ds_read_b128 v[26:29], v226
	ds_read_b128 v[30:33], v226 offset:1024
	ds_read_b128 v[66:69], v226 offset:2048
	ds_read_b128 v[70:73], v226 offset:3072
	ds_read_b128 v[164:167], v227
	ds_read_b128 v[168:171], v227 offset:1024
	ds_read_b128 v[172:175], v227 offset:2048
	ds_read_b128 v[176:179], v227 offset:3072
	s_add_i32 s13, s13, 0x100000
	s_mov_b32 m0, s74
	ds_read_b128 v[74:77], v194 offset:32768
	ds_read_b128 v[78:81], v194 offset:33792
	ds_read_b128 v[116:119], v194 offset:34816
	ds_read_b128 v[120:123], v194 offset:35840
	ds_read_b128 v[180:183], v194 offset:36864
	ds_read_b128 v[184:187], v194 offset:37888
	ds_read_b128 v[196:199], v194 offset:38912
	ds_read_b128 v[200:203], v194 offset:39936
	buffer_load_dwordx4 v115, s[40:43], s13 offen lds
	s_mov_b32 m0, s75
	s_nop 0
	buffer_load_dwordx4 v189, s[40:43], s13 offen lds
	s_waitcnt vmcnt(8)
	s_waitcnt lgkmcnt(0)
	s_barrier
	s_waitcnt lgkmcnt(7)
	v_mfma_f32_16x16x32_bf16 v[46:49], v[26:29], v[74:77], v[46:49]
	v_mfma_f32_16x16x32_bf16 v[42:45], v[66:69], v[74:77], v[42:45]
	s_waitcnt lgkmcnt(5)
	v_mfma_f32_16x16x32_bf16 v[160:163], v[26:29], v[116:119], v[160:163]
	v_mfma_f32_16x16x32_bf16 v[156:159], v[66:69], v[116:119], v[156:159]
	s_waitcnt lgkmcnt(3)
	v_mfma_f32_16x16x32_bf16 v[144:147], v[26:29], v[180:183], v[144:147]
	v_mfma_f32_16x16x32_bf16 v[140:143], v[66:69], v[180:183], v[140:143]
	s_waitcnt lgkmcnt(1)
	v_mfma_f32_16x16x32_bf16 v[62:65], v[26:29], v[196:199], v[62:65]
	v_mfma_f32_16x16x32_bf16 v[58:61], v[66:69], v[196:199], v[58:61]
	v_mfma_f32_16x16x32_bf16 v[46:49], v[30:33], v[78:81], v[46:49]
	v_mfma_f32_16x16x32_bf16 v[42:45], v[70:73], v[78:81], v[42:45]
	v_mfma_f32_16x16x32_bf16 v[160:163], v[30:33], v[120:123], v[160:163]
	v_mfma_f32_16x16x32_bf16 v[156:159], v[70:73], v[120:123], v[156:159]
	v_mfma_f32_16x16x32_bf16 v[144:147], v[30:33], v[184:187], v[144:147]
	v_mfma_f32_16x16x32_bf16 v[140:143], v[70:73], v[184:187], v[140:143]
	s_waitcnt lgkmcnt(0)
	v_mfma_f32_16x16x32_bf16 v[62:65], v[30:33], v[200:203], v[62:65]
	v_mfma_f32_16x16x32_bf16 v[58:61], v[70:73], v[200:203], v[58:61]
	v_mfma_f32_16x16x32_bf16 v[38:41], v[164:167], v[74:77], v[38:41]
	v_mfma_f32_16x16x32_bf16 v[34:37], v[172:175], v[74:77], v[34:37]
	v_mfma_f32_16x16x32_bf16 v[74:77], v[164:167], v[116:119], v[152:155]
	v_mfma_f32_16x16x32_bf16 v[152:155], v[168:171], v[120:123], v[74:77]
	v_mfma_f32_16x16x32_bf16 v[74:77], v[172:175], v[116:119], v[148:151]
	v_mfma_f32_16x16x32_bf16 v[148:151], v[176:179], v[120:123], v[74:77]
	v_mfma_f32_16x16x32_bf16 v[74:77], v[164:167], v[180:183], v[136:139]
	v_mfma_f32_16x16x32_bf16 v[136:139], v[168:171], v[184:187], v[74:77]
	v_mfma_f32_16x16x32_bf16 v[74:77], v[172:175], v[180:183], v[132:135]
	v_mfma_f32_16x16x32_bf16 v[54:57], v[164:167], v[196:199], v[54:57]
	v_mfma_f32_16x16x32_bf16 v[50:53], v[172:175], v[196:199], v[50:53]
	v_mfma_f32_16x16x32_bf16 v[38:41], v[168:171], v[78:81], v[38:41]
	v_mfma_f32_16x16x32_bf16 v[34:37], v[176:179], v[78:81], v[34:37]
	v_mfma_f32_16x16x32_bf16 v[132:135], v[176:179], v[184:187], v[74:77]
	v_mfma_f32_16x16x32_bf16 v[54:57], v[168:171], v[200:203], v[54:57]
	v_mfma_f32_16x16x32_bf16 v[50:53], v[176:179], v[200:203], v[50:53]
	s_barrier
	s_mov_b32 m0, s85
	s_or_b32 s13, s12, 0x80
	ds_read_b128 v[116:119], v194 offset:49152
	ds_read_b128 v[180:183], v194 offset:50176
	ds_read_b128 v[184:187], v194 offset:51200
	ds_read_b128 v[196:199], v194 offset:52224
	ds_read_b128 v[200:203], v194 offset:53248
	ds_read_b128 v[204:207], v194 offset:54272
	ds_read_b128 v[208:211], v194 offset:55296
	ds_read_b128 v[220:223], v194 offset:56320
	buffer_load_dwordx4 v188, s[44:47], s13 offen lds
	s_mov_b32 m0, s93
	s_add_i32 s12, s12, 0x40080
	buffer_load_dwordx4 v190, s[44:47], s13 offen lds
	s_mov_b32 m0, s67
	s_nop 0
	buffer_load_dwordx4 v188, s[44:47], s12 offen lds
	s_mov_b32 m0, s49
	s_nop 0
	buffer_load_dwordx4 v190, s[44:47], s12 offen lds
	s_mov_b32 m0, s94
	s_nop 0
	buffer_load_dwordx4 v115, s[40:43], s11 offen lds
	s_mov_b32 m0, s95
	s_nop 0
	buffer_load_dwordx4 v189, s[40:43], s11 offen lds
	s_add_i32 s10, s10, 2
	s_addk_i32 s4, 0x100
	s_addk_i32 s5, 0x100
	s_waitcnt vmcnt(8)
	s_waitcnt lgkmcnt(0)
	s_barrier
	s_waitcnt lgkmcnt(7)
	v_mfma_f32_16x16x32_bf16 v[74:77], v[26:29], v[116:119], v[128:131]
	s_waitcnt lgkmcnt(6)
	v_mfma_f32_16x16x32_bf16 v[128:131], v[30:33], v[180:183], v[74:77]
	v_mfma_f32_16x16x32_bf16 v[74:77], v[66:69], v[116:119], v[124:127]
	v_mfma_f32_16x16x32_bf16 v[124:127], v[70:73], v[180:183], v[74:77]
	s_waitcnt lgkmcnt(5)
	v_mfma_f32_16x16x32_bf16 v[74:77], v[26:29], v[184:187], v[110:113]
	s_waitcnt lgkmcnt(4)
	v_mfma_f32_16x16x32_bf16 v[110:113], v[30:33], v[196:199], v[74:77]
	v_mfma_f32_16x16x32_bf16 v[74:77], v[66:69], v[184:187], v[106:109]
	v_mfma_f32_16x16x32_bf16 v[106:109], v[70:73], v[196:199], v[74:77]
	s_waitcnt lgkmcnt(3)
	v_mfma_f32_16x16x32_bf16 v[74:77], v[26:29], v[200:203], v[94:97]
	s_waitcnt lgkmcnt(1)
	v_mfma_f32_16x16x32_bf16 v[2:5], v[26:29], v[208:211], v[2:5]
	v_mfma_f32_16x16x32_bf16 v[94:97], v[30:33], v[204:207], v[74:77]
	v_mfma_f32_16x16x32_bf16 v[74:77], v[66:69], v[200:203], v[90:93]
	s_waitcnt lgkmcnt(0)
	v_mfma_f32_16x16x32_bf16 v[78:81], v[30:33], v[220:223], v[2:5]
	v_mfma_f32_16x16x32_bf16 v[2:5], v[66:69], v[208:211], v[6:9]
	v_mfma_f32_16x16x32_bf16 v[90:93], v[70:73], v[204:207], v[74:77]
	v_mfma_f32_16x16x32_bf16 v[74:77], v[70:73], v[220:223], v[2:5]
	v_mfma_f32_16x16x32_bf16 v[2:5], v[164:167], v[116:119], v[10:13]
	v_mfma_f32_16x16x32_bf16 v[120:123], v[168:171], v[180:183], v[2:5]
	v_mfma_f32_16x16x32_bf16 v[2:5], v[172:175], v[116:119], v[14:17]
	v_mfma_f32_16x16x32_bf16 v[116:119], v[176:179], v[180:183], v[2:5]
	v_mfma_f32_16x16x32_bf16 v[2:5], v[164:167], v[184:187], v[102:105]
	v_mfma_f32_16x16x32_bf16 v[102:105], v[168:171], v[196:199], v[2:5]
	v_mfma_f32_16x16x32_bf16 v[2:5], v[172:175], v[184:187], v[98:101]
	v_mfma_f32_16x16x32_bf16 v[98:101], v[176:179], v[196:199], v[2:5]
	v_mfma_f32_16x16x32_bf16 v[2:5], v[164:167], v[200:203], v[86:89]
	v_mfma_f32_16x16x32_bf16 v[86:89], v[168:171], v[204:207], v[2:5]
	v_mfma_f32_16x16x32_bf16 v[2:5], v[172:175], v[200:203], v[82:85]
	v_mfma_f32_16x16x32_bf16 v[82:85], v[176:179], v[204:207], v[2:5]
	v_mfma_f32_16x16x32_bf16 v[2:5], v[164:167], v[208:211], v[18:21]
	v_mfma_f32_16x16x32_bf16 v[70:73], v[168:171], v[220:223], v[2:5]
	v_mfma_f32_16x16x32_bf16 v[2:5], v[172:175], v[208:211], v[22:25]
	v_mfma_f32_16x16x32_bf16 v[66:69], v[176:179], v[220:223], v[2:5]
	s_barrier
	s_cmp_gt_u32 s10, 61
	s_cbranch_scc0 .LBB0_137
	v_readlane_b32 s2, v255, 30
	v_readlane_b32 s3, v255, 31
	s_and_b64 vcc, exec, s[2:3]
	s_cbranch_vccz .LBB0_140
	s_barrier
